# sample recurrent step: gate-weight/state/bias loads issued with the conv operands (3 dependent round trips -> 1)
# baseline (speedup 1.0000x reference)
.LBB0_1865:
	s_or_b64 exec, exec, s[0:1]
	v_readlane_b32 s0, v254, 37
	s_add_i32 s0, s0, s6
	s_ashr_i32 s1, s0, 31
	s_lshl_b64 s[0:1], s[0:1], 16
	v_lshl_add_u64 v[0:1], v[124:125], 0, s[0:1]
	v_mov_b64_e32 v[24:25], v[168:169]
	v_mov_b64_e32 v[26:27], v[170:171]
	v_add_co_u32_e32 v4, vcc, 0x8000, v0
	v_readlane_b32 s2, v253, 37
	s_nop 0
	v_addc_co_u32_e32 v5, vcc, 0, v1, vcc
	v_mov_b64_e32 v[28:29], v[172:173]
	v_mov_b64_e32 v[30:31], v[174:175]
	v_mov_b64_e32 v[16:17], v[176:177]
	v_mov_b64_e32 v[18:19], v[178:179]
	v_mov_b64_e32 v[20:21], v[180:181]
	v_mov_b64_e32 v[22:23], v[182:183]
	v_mov_b64_e32 v[8:9], v[184:185]
	v_mov_b64_e32 v[10:11], v[186:187]
	v_mov_b64_e32 v[12:13], v[188:189]
	v_mov_b64_e32 v[14:15], v[190:191]
	s_nop 0
	v_mov_b64_e32 v[0:1], v[192:193]
	v_mov_b64_e32 v[2:3], v[194:195]
	s_nop 0
	v_mov_b64_e32 v[4:5], v[196:197]
	v_mov_b64_e32 v[6:7], v[198:199]
	v_add_u32_e32 v38, s2, v87
	v_ashrrev_i32_e32 v39, 31, v38
	v_readlane_b32 s76, v251, 1
	v_lshlrev_b64 v[80:81], 2, v[38:39]
	v_readlane_b32 s86, v251, 11
	v_readlane_b32 s87, v251, 12
	v_mul_f32_e32 v36, 0xc1000000, v36
	v_add_u32_e32 v106, v226, v233
	v_lshl_add_u64 v[38:39], s[86:87], 0, v[80:81]
	v_lshl_add_u64 v[40:41], v[38:39], 0, v[44:45]
	v_mov_b32_e32 v116, v200
	v_add_u32_e32 v40, s2, v89
	v_ashrrev_i32_e32 v41, 31, v40
	v_lshl_add_u64 v[82:83], v[40:41], 2, s[52:53]
	v_mov_b32_e32 v117, v201
	v_lshl_add_u64 v[82:83], v[38:39], 0, v[46:47]
	v_mov_b32_e32 v109, v202
	v_add_u32_e32 v82, 0x800, v40
	v_ashrrev_i32_e32 v83, 31, v82
	v_lshl_add_u64 v[82:83], v[82:83], 2, s[52:53]
	v_mov_b32_e32 v108, v203
	v_lshl_add_u64 v[82:83], v[38:39], 0, v[48:49]
	v_mov_b32_e32 v107, v204
	v_add_u32_e32 v82, 0x1000, v40
	v_ashrrev_i32_e32 v83, 31, v82
	v_lshl_add_u64 v[82:83], v[82:83], 2, s[52:53]
	v_mov_b32_e32 v105, v205
	v_lshl_add_u64 v[82:83], v[38:39], 0, v[50:51]
	v_mov_b32_e32 v104, v206
	v_add_u32_e32 v82, 0x1800, v40
	v_ashrrev_i32_e32 v83, 31, v82
	v_lshl_add_u64 v[82:83], v[82:83], 2, s[52:53]
	v_mov_b32_e32 v103, v207
	v_lshl_add_u64 v[82:83], v[38:39], 0, v[52:53]
	v_mov_b32_e32 v102, v208
	v_add_u32_e32 v82, 0x8000, v40
	v_ashrrev_i32_e32 v83, 31, v82
	v_lshl_add_u64 v[82:83], v[82:83], 2, s[52:53]
	v_mul_f32_e32 v99, 0xbfb8aa3b, v35
	v_mul_f32_e32 v98, 0xbfb8aa3b, v34
	v_mul_f32_e32 v97, 0x3fb8aa3b, v36
	ds_read_b128 v[34:37], v106 offset:33792
	ds_read_b128 v[110:113], v106 offset:33856
	v_mov_b32_e32 v101, v209
	v_lshl_add_u64 v[82:83], v[38:39], 0, v[54:55]
	v_mov_b32_e32 v100, v210
	v_add_u32_e32 v82, 0x8800, v40
	v_ashrrev_i32_e32 v83, 31, v82
	v_lshl_add_u64 v[82:83], v[82:83], 2, s[52:53]
	v_mov_b32_e32 v96, v211
	v_lshl_add_u64 v[82:83], v[38:39], 0, v[56:57]
	v_lshl_add_u64 v[38:39], v[38:39], 0, v[58:59]
	v_mov_b32_e32 v95, v212
	v_mov_b32_e32 v93, v213
	v_add_u32_e32 v82, 0x9000, v40
	v_add_u32_e32 v38, 0x9800, v40
	v_ashrrev_i32_e32 v83, 31, v82
	v_ashrrev_i32_e32 v39, 31, v38
	v_lshl_add_u64 v[82:83], v[82:83], 2, s[52:53]
	v_lshl_add_u64 v[38:39], v[38:39], 2, s[52:53]
	v_mov_b32_e32 v94, v236
	v_mov_b32_e32 v92, v237
	s_add_i32 s6, s6, s15
	v_add_u32_e32 v89, s5, v89
	v_add_u32_e32 v87, s5, v87
	v_add_u32_e32 v90, s5, v90
	v_add_u32_e32 v84, s5, v84
	s_cmp_lt_i32 s6, 8
	v_readlane_b32 s77, v251, 2
	v_readlane_b32 s78, v251, 3
	v_readlane_b32 s79, v251, 4
	v_readlane_b32 s80, v251, 5
	v_readlane_b32 s81, v251, 6
	s_waitcnt vmcnt(23) lgkmcnt(1)
	v_mfma_f32_16x16x32_bf16 v[38:41], v[34:37], v[24:27], 0
	v_readlane_b32 s82, v251, 7
	v_readlane_b32 s83, v251, 8
	v_readlane_b32 s84, v251, 9
	s_waitcnt vmcnt(22)
	v_mfma_f32_16x16x32_bf16 v[34:37], v[34:37], v[28:31], 0
	ds_read_b32 v82, v235
	v_readlane_b32 s85, v251, 10
	v_readlane_b32 s88, v251, 13
	s_waitcnt vmcnt(21) lgkmcnt(1)
	v_mfma_f32_16x16x32_bf16 v[38:41], v[110:113], v[16:19], v[38:41]
	v_readlane_b32 s89, v251, 14
	v_readlane_b32 s90, v251, 15
	v_readlane_b32 s91, v251, 16
	s_waitcnt vmcnt(20)
	v_mfma_f32_16x16x32_bf16 v[34:37], v[110:113], v[20:23], v[34:37]
	ds_read_b128 v[110:113], v106 offset:33920
	s_waitcnt vmcnt(19) lgkmcnt(0)
	v_mfma_f32_16x16x32_bf16 v[38:41], v[110:113], v[8:11], v[38:41]
	s_waitcnt vmcnt(18)
	v_mfma_f32_16x16x32_bf16 v[34:37], v[110:113], v[12:15], v[34:37]
	ds_read_b128 v[110:113], v106 offset:33984
	s_waitcnt vmcnt(17) lgkmcnt(0)
	v_mfma_f32_16x16x32_bf16 v[38:41], v[110:113], v[0:3], v[38:41]
	s_nop 7
	v_fmamk_f32 v38, v38, 0xbfb8aa3b, v99
	v_exp_f32_e32 v38, v38
	s_waitcnt vmcnt(16)
	v_mfma_f32_16x16x32_bf16 v[34:37], v[110:113], v[4:7], v[34:37]
	v_add_f32_e32 v38, 1.0, v38
	v_rcp_f32_e32 v38, v38
	s_nop 0
	v_mul_f32_e32 v38, v97, v38
	s_nop 3
	v_fmamk_f32 v34, v34, 0xbfb8aa3b, v98
	v_exp_f32_e32 v34, v34
	v_exp_f32_e32 v38, v38
	v_fmamk_f32 v35, v35, 0xbfb8aa3b, v98
	v_exp_f32_e32 v35, v35
	v_add_f32_e32 v34, 1.0, v34
	v_fma_f32 v83, -v38, v38, 1.0
	v_rcp_f32_e32 v34, v34
	v_max_f32_e32 v83, 0, v83
	v_sqrt_f32_e32 v83, v83
	v_add_f32_e32 v35, 1.0, v35
	v_mul_f32_e32 v34, v82, v34
	v_rcp_f32_e32 v35, v35
	v_mul_f32_e32 v34, v34, v83
	s_waitcnt vmcnt(15)
	v_fmac_f32_e32 v34, v116, v38
	s_waitcnt vmcnt(14)
	v_mul_f32_e32 v38, 0x3d372713, v117
	v_mul_f32_e32 v38, v117, v38
	v_fma_f32 v38, v117, v38, v117
	v_mul_f32_e32 v38, 0x3fcc422a, v38
	v_mul_f32_e32 v38, 0xbfb8aa3b, v38
	v_exp_f32_e32 v38, v38
	v_lshl_add_u64 v[82:83], v[64:65], 0, v[80:81]
	global_store_dword v[82:83], v34, off
	v_add_u32_e32 v82, s2, v88
	v_add_f32_e32 v38, 1.0, v38
	v_rcp_f32_e32 v38, v38
	v_ashrrev_i32_e32 v83, 31, v82
	v_lshl_add_u64 v[110:111], v[82:83], 1, s[54:55]
	v_fmamk_f32 v36, v36, 0xbfb8aa3b, v98
	v_mul_f32_e32 v38, v117, v38
	v_mul_f32_e32 v34, v38, v34
	v_fmamk_f32 v38, v39, 0xbfb8aa3b, v99
	v_exp_f32_e32 v38, v38
	v_cvt_pk_bf16_f32 v34, v34, v33
	global_store_short v[110:111], v34, off
	ds_read_b32 v34, v91 offset:43280
	v_add_f32_e32 v38, 1.0, v38
	v_rcp_f32_e32 v38, v38
	v_exp_f32_e32 v36, v36
	v_add_u32_e32 v88, s5, v88
	s_waitcnt lgkmcnt(0)
	v_mul_f32_e32 v34, v35, v34
	v_mul_f32_e32 v38, v97, v38
	v_exp_f32_e32 v38, v38
	v_add_f32_e32 v36, 1.0, v36
	v_rcp_f32_e32 v36, v36
	v_fma_f32 v39, -v38, v38, 1.0
	v_max_f32_e32 v39, 0, v39
	v_sqrt_f32_e32 v39, v39
	s_nop 0
	v_mul_f32_e32 v39, v34, v39
	s_waitcnt vmcnt(15)
	v_fmac_f32_e32 v39, v109, v38
	v_lshl_add_u64 v[34:35], v[66:67], 0, v[80:81]
	global_store_dword v[34:35], v39, off
	s_waitcnt vmcnt(15)
	v_mul_f32_e32 v34, 0x3d372713, v108
	v_mul_f32_e32 v34, v108, v34
	v_fma_f32 v34, v108, v34, v108
	v_mul_f32_e32 v34, 0x3fcc422a, v34
	v_mul_f32_e32 v34, 0xbfb8aa3b, v34
	v_exp_f32_e32 v34, v34
	s_nop 0
	v_add_f32_e32 v34, 1.0, v34
	v_rcp_f32_e32 v34, v34
	s_nop 0
	v_mul_f32_e32 v34, v108, v34
	v_mul_f32_e32 v34, v34, v39
	v_cvt_pk_bf16_f32 v38, v34, v33
	v_add_u32_e32 v34, 0x400, v82
	v_ashrrev_i32_e32 v35, 31, v34
	v_lshl_add_u64 v[34:35], v[34:35], 1, s[54:55]
	global_store_short v[34:35], v38, off
	v_fmamk_f32 v35, v40, 0xbfb8aa3b, v99
	v_exp_f32_e32 v35, v35
	ds_read_b32 v34, v91 offset:43808
	v_add_f32_e32 v35, 1.0, v35
	v_rcp_f32_e32 v35, v35
	s_waitcnt lgkmcnt(0)
	v_mul_f32_e32 v34, v36, v34
	v_mul_f32_e32 v35, v97, v35
	v_exp_f32_e32 v35, v35
	s_nop 0
	v_fma_f32 v38, -v35, v35, 1.0
	v_max_f32_e32 v38, 0, v38
	v_sqrt_f32_e32 v38, v38
	s_nop 0
	v_mul_f32_e32 v36, v38, v34
	s_waitcnt vmcnt(15)
	v_fmac_f32_e32 v36, v107, v35
	v_lshl_add_u64 v[34:35], v[68:69], 0, v[80:81]
	global_store_dword v[34:35], v36, off
	s_waitcnt vmcnt(15)
	v_mul_f32_e32 v34, 0x3d372713, v105
	v_mul_f32_e32 v34, v105, v34
	v_fma_f32 v34, v105, v34, v105
	v_mul_f32_e32 v34, 0x3fcc422a, v34
	v_mul_f32_e32 v34, 0xbfb8aa3b, v34
	v_exp_f32_e32 v34, v34
	s_nop 0
	v_add_f32_e32 v34, 1.0, v34
	v_rcp_f32_e32 v34, v34
	s_nop 0
	v_mul_f32_e32 v34, v105, v34
	v_mul_f32_e32 v34, v34, v36
	v_cvt_pk_bf16_f32 v36, v34, v33
	v_add_u32_e32 v34, 0x800, v82
	v_ashrrev_i32_e32 v35, 31, v34
	v_lshl_add_u64 v[34:35], v[34:35], 1, s[54:55]
	global_store_short v[34:35], v36, off
	v_fmamk_f32 v35, v41, 0xbfb8aa3b, v99
	v_exp_f32_e32 v35, v35
	v_fmamk_f32 v36, v37, 0xbfb8aa3b, v98
	v_exp_f32_e32 v36, v36
	ds_read_b32 v34, v91 offset:44336
	v_add_f32_e32 v35, 1.0, v35
	v_rcp_f32_e32 v35, v35
	v_add_f32_e32 v36, 1.0, v36
	v_rcp_f32_e32 v36, v36
	v_mul_f32_e32 v35, v97, v35
	v_exp_f32_e32 v35, v35
	s_waitcnt lgkmcnt(0)
	v_mul_f32_e32 v34, v36, v34
	v_fma_f32 v37, -v35, v35, 1.0
	v_max_f32_e32 v37, 0, v37
	v_sqrt_f32_e32 v37, v37
	s_nop 0
	v_mul_f32_e32 v36, v37, v34
	s_waitcnt vmcnt(15)
	v_fmac_f32_e32 v36, v104, v35
	v_lshl_add_u64 v[34:35], v[70:71], 0, v[80:81]
	global_store_dword v[34:35], v36, off
	s_waitcnt vmcnt(15)
	v_mul_f32_e32 v34, 0x3d372713, v103
	v_mul_f32_e32 v34, v103, v34
	v_fma_f32 v34, v103, v34, v103
	v_mul_f32_e32 v34, 0x3fcc422a, v34
	v_mul_f32_e32 v34, 0xbfb8aa3b, v34
	v_exp_f32_e32 v34, v34
	s_nop 0
	v_add_f32_e32 v34, 1.0, v34
	v_rcp_f32_e32 v34, v34
	s_nop 0
	v_mul_f32_e32 v34, v103, v34
	v_mul_f32_e32 v34, v34, v36
	v_cvt_pk_bf16_f32 v36, v34, v33
	v_add_u32_e32 v34, 0xc00, v82
	v_ashrrev_i32_e32 v35, 31, v34
	v_lshl_add_u64 v[34:35], v[34:35], 1, s[54:55]
	global_store_short v[34:35], v36, off
	ds_read_b128 v[34:37], v106 offset:38144
	s_waitcnt lgkmcnt(0)
	v_mfma_f32_16x16x32_bf16 v[24:27], v[34:37], v[24:27], 0
	v_mfma_f32_16x16x32_bf16 v[28:31], v[34:37], v[28:31], 0
	ds_read_b128 v[34:37], v106 offset:38208
	s_waitcnt lgkmcnt(0)
	v_mfma_f32_16x16x32_bf16 v[16:19], v[34:37], v[16:19], v[24:27]
	s_nop 3
	ds_read_b128 v[24:27], v106 offset:38272
	s_waitcnt lgkmcnt(0)
	v_mfma_f32_16x16x32_bf16 v[8:11], v[24:27], v[8:11], v[16:19]
	s_nop 2
	ds_read_b128 v[16:19], v106 offset:38336
	v_mfma_f32_16x16x32_bf16 v[20:23], v[34:37], v[20:23], v[28:31]
	v_mfma_f32_16x16x32_bf16 v[12:15], v[24:27], v[12:15], v[20:23]
	s_waitcnt lgkmcnt(0)
	v_mfma_f32_16x16x32_bf16 v[8:11], v[16:19], v[0:3], v[8:11]
	v_mfma_f32_16x16x32_bf16 v[0:3], v[16:19], v[4:7], v[12:15]
	ds_read_b32 v4, v91 offset:51200
	s_nop 5
	v_fmamk_f32 v5, v8, 0xbfb8aa3b, v99
	v_exp_f32_e32 v5, v5
	s_nop 0
	v_add_f32_e32 v5, 1.0, v5
	v_rcp_f32_e32 v5, v5
	v_fmamk_f32 v0, v0, 0xbfb8aa3b, v98
	v_exp_f32_e32 v0, v0
	v_fmamk_f32 v1, v1, 0xbfb8aa3b, v98
	v_mul_f32_e32 v5, v97, v5
	v_exp_f32_e32 v5, v5
	v_add_f32_e32 v0, 1.0, v0
	v_rcp_f32_e32 v0, v0
	v_exp_f32_e32 v1, v1
	v_fma_f32 v6, -v5, v5, 1.0
	v_max_f32_e32 v6, 0, v6
	v_sqrt_f32_e32 v6, v6
	s_waitcnt lgkmcnt(0)
	v_mul_f32_e32 v0, v4, v0
	v_add_f32_e32 v1, 1.0, v1
	v_rcp_f32_e32 v1, v1
	v_mul_f32_e32 v0, v0, v6
	s_waitcnt vmcnt(15)
	v_fmac_f32_e32 v0, v102, v5
	v_lshl_add_u64 v[4:5], v[72:73], 0, v[80:81]
	global_store_dword v[4:5], v0, off
	s_waitcnt vmcnt(15)
	v_mul_f32_e32 v4, 0x3d372713, v101
	v_mul_f32_e32 v4, v101, v4
	v_fma_f32 v4, v101, v4, v101
	v_mul_f32_e32 v4, 0x3fcc422a, v4
	v_mul_f32_e32 v4, 0xbfb8aa3b, v4
	v_exp_f32_e32 v4, v4
	v_fmamk_f32 v2, v2, 0xbfb8aa3b, v98
	v_exp_f32_e32 v2, v2
	v_fmac_f32_e32 v98, 0xbfb8aa3b, v3
	v_add_f32_e32 v4, 1.0, v4
	v_rcp_f32_e32 v4, v4
	v_add_f32_e32 v2, 1.0, v2
	v_rcp_f32_e32 v2, v2
	v_mul_f32_e32 v4, v101, v4
	v_mul_f32_e32 v0, v4, v0
	v_add_u32_e32 v4, 0x4000, v82
	v_ashrrev_i32_e32 v5, 31, v4
	v_lshl_add_u64 v[4:5], v[4:5], 1, s[54:55]
	v_cvt_pk_bf16_f32 v0, v0, v33
	global_store_short v[4:5], v0, off
	v_fmamk_f32 v4, v9, 0xbfb8aa3b, v99
	v_exp_f32_e32 v4, v4
	ds_read_b32 v0, v91 offset:51728
	v_add_f32_e32 v4, 1.0, v4
	v_rcp_f32_e32 v4, v4
	s_waitcnt lgkmcnt(0)
	v_mul_f32_e32 v0, v1, v0
	v_mul_f32_e32 v4, v97, v4
	v_exp_f32_e32 v4, v4
	s_nop 0
	v_fma_f32 v5, -v4, v4, 1.0
	v_max_f32_e32 v5, 0, v5
	v_sqrt_f32_e32 v5, v5
	s_nop 0
	v_mul_f32_e32 v5, v0, v5
	s_waitcnt vmcnt(15)
	v_fmac_f32_e32 v5, v100, v4
	v_lshl_add_u64 v[0:1], v[74:75], 0, v[80:81]
	global_store_dword v[0:1], v5, off
	s_waitcnt vmcnt(15)
	v_mul_f32_e32 v0, 0x3d372713, v96
	v_mul_f32_e32 v0, v96, v0
	v_fma_f32 v0, v96, v0, v96
	v_mul_f32_e32 v0, 0x3fcc422a, v0
	v_mul_f32_e32 v0, 0xbfb8aa3b, v0
	v_exp_f32_e32 v0, v0
	s_nop 0
	v_add_f32_e32 v0, 1.0, v0
	v_rcp_f32_e32 v0, v0
	s_nop 0
	v_mul_f32_e32 v0, v96, v0
	v_mul_f32_e32 v0, v0, v5
	v_cvt_pk_bf16_f32 v4, v0, v33
	v_add_u32_e32 v0, 0x4400, v82
	v_ashrrev_i32_e32 v1, 31, v0
	v_lshl_add_u64 v[0:1], v[0:1], 1, s[54:55]
	global_store_short v[0:1], v4, off
	v_fmamk_f32 v1, v10, 0xbfb8aa3b, v99
	v_exp_f32_e32 v1, v1
	ds_read_b32 v0, v91 offset:52256
	v_fmac_f32_e32 v99, 0xbfb8aa3b, v11
	v_add_f32_e32 v1, 1.0, v1
	v_rcp_f32_e32 v1, v1
	s_waitcnt lgkmcnt(0)
	v_mul_f32_e32 v0, v2, v0
	v_mul_f32_e32 v1, v97, v1
	v_exp_f32_e32 v1, v1
	s_nop 0
	v_fma_f32 v4, -v1, v1, 1.0
	v_max_f32_e32 v4, 0, v4
	v_sqrt_f32_e32 v4, v4
	s_nop 0
	v_mul_f32_e32 v2, v4, v0
	s_waitcnt vmcnt(15)
	v_fmac_f32_e32 v2, v95, v1
	v_lshl_add_u64 v[0:1], v[76:77], 0, v[80:81]
	global_store_dword v[0:1], v2, off
	s_waitcnt vmcnt(14)
	v_mul_f32_e32 v0, 0x3d372713, v94
	v_mul_f32_e32 v0, v94, v0
	v_fma_f32 v0, v94, v0, v94
	v_mul_f32_e32 v0, 0x3fcc422a, v0
	v_mul_f32_e32 v0, 0xbfb8aa3b, v0
	v_exp_f32_e32 v0, v0
	s_nop 0
	v_add_f32_e32 v0, 1.0, v0
	v_rcp_f32_e32 v0, v0
	s_nop 0
	v_mul_f32_e32 v0, v94, v0
	v_mul_f32_e32 v0, v0, v2
	v_cvt_pk_bf16_f32 v2, v0, v33
	v_add_u32_e32 v0, 0x4800, v82
	v_ashrrev_i32_e32 v1, 31, v0
	v_lshl_add_u64 v[0:1], v[0:1], 1, s[54:55]
	global_store_short v[0:1], v2, off
	v_exp_f32_e32 v1, v99
	v_exp_f32_e32 v2, v98
	ds_read_b32 v0, v91 offset:52784
	v_add_f32_e32 v1, 1.0, v1
	v_rcp_f32_e32 v1, v1
	v_add_f32_e32 v2, 1.0, v2
	v_rcp_f32_e32 v2, v2
	v_mul_f32_e32 v1, v97, v1
	v_exp_f32_e32 v1, v1
	s_waitcnt lgkmcnt(0)
	v_mul_f32_e32 v0, v2, v0
	v_fma_f32 v3, -v1, v1, 1.0
	v_max_f32_e32 v3, 0, v3
	v_sqrt_f32_e32 v3, v3
	s_nop 0
	v_mul_f32_e32 v2, v3, v0
	v_fmac_f32_e32 v2, v93, v1
	v_lshl_add_u64 v[0:1], v[78:79], 0, v[80:81]
	global_store_dword v[0:1], v2, off
	s_waitcnt vmcnt(15)
	v_mul_f32_e32 v0, 0x3d372713, v92
	v_mul_f32_e32 v0, v92, v0
	v_fma_f32 v0, v92, v0, v92
	v_mul_f32_e32 v0, 0x3fcc422a, v0
	v_mul_f32_e32 v0, 0xbfb8aa3b, v0
	v_exp_f32_e32 v0, v0
	s_nop 0
	v_add_f32_e32 v0, 1.0, v0
	v_rcp_f32_e32 v0, v0
	s_nop 0
	v_mul_f32_e32 v0, v92, v0
	v_mul_f32_e32 v0, v0, v2
	v_cvt_pk_bf16_f32 v2, v0, v33
	v_add_u32_e32 v0, 0x4c00, v82
	v_ashrrev_i32_e32 v1, 31, v0
	v_lshl_add_u64 v[0:1], v[0:1], 1, s[54:55]
	global_store_short v[0:1], v2, off
	s_cbranch_scc0 .LBB0_1872
.LBB0_1866:
	v_add_u32_e32 v0, s2, v84
	v_ashrrev_i32_e32 v1, 31, v0
	v_lshlrev_b64 v[112:113], 2, v[0:1]
	v_lshl_add_u64 v[16:17], v[60:61], 0, v[112:113]
	s_movk_i32 s3, 0x2000
	v_add_co_u32_e32 v18, vcc, s3, v16
	s_mov_b64 s[0:1], 0x2000
	s_nop 0
	v_addc_co_u32_e32 v19, vcc, 0, v17, vcc
	v_lshl_add_u64 v[104:105], s[56:57], 0, v[112:113]
	s_mov_b64 s[12:13], 0x1000
	v_lshl_add_u64 v[20:21], v[16:17], 0, s[0:1]
	v_add_co_u32_e32 v96, vcc, s3, v104
	v_lshl_add_u64 v[100:101], v[104:105], 0, s[0:1]
	s_mov_b64 s[0:1], 0x3000
	v_lshl_add_u64 v[12:13], v[16:17], 0, s[12:13]
	v_lshl_add_u64 v[28:29], v[42:43], 0, v[112:113]
	v_addc_co_u32_e32 v97, vcc, 0, v105, vcc
	v_lshl_add_u64 v[108:109], v[104:105], 0, s[0:1]
	s_movk_i32 s0, 0x3000
	s_barrier
	v_readlane_b32 s100, v254, 37
	s_nop 1
	s_add_i32 s100, s100, s6
	s_ashr_i32 s101, s100, 31
	s_lshl_b64 s[100:101], s[100:101], 16
	v_lshl_add_u64 v[144:145], v[124:125], 0, s[100:101]
	v_add_co_u32_e32 v146, vcc, 0x8000, v144
	s_nop 1
	v_addc_co_u32_e32 v147, vcc, 0, v145, vcc
	global_load_dwordx4 v[168:171], v[144:145], off
	global_load_dwordx4 v[172:175], v[146:147], off
	global_load_dwordx4 v[176:179], v[144:145], off offset:64
	global_load_dwordx4 v[180:183], v[146:147], off offset:64
	global_load_dwordx4 v[184:187], v[144:145], off offset:128
	global_load_dwordx4 v[188:191], v[146:147], off offset:128
	global_load_dwordx4 v[192:195], v[144:145], off offset:192
	global_load_dwordx4 v[196:199], v[146:147], off offset:192
	v_readlane_b32 s100, v253, 37
	s_nop 3
	v_add_u32_e32 v148, s100, v87
	v_ashrrev_i32_e32 v149, 31, v148
	v_lshlrev_b64 v[148:149], 2, v[148:149]
	v_add_u32_e32 v150, s100, v89
	v_ashrrev_i32_e32 v151, 31, v150
	v_add_u32_e32 v160, s100, v90
	v_ashrrev_i32_e32 v161, 31, v160
	v_lshlrev_b64 v[160:161], 2, v[160:161]
	v_readlane_b32 s100, v251, 11
	v_readlane_b32 s101, v251, 12
	s_nop 3
	v_lshl_add_u64 v[148:149], s[100:101], 0, v[148:149]
	v_lshl_add_u64 v[152:153], v[148:149], 0, v[44:45]
	global_load_dword v200, v[152:153], off
	v_lshl_add_u64 v[152:153], v[150:151], 2, s[52:53]
	global_load_dword v201, v[152:153], off
	v_lshl_add_u64 v[152:153], v[148:149], 0, v[46:47]
	global_load_dword v202, v[152:153], off
	v_add_u32_e32 v152, 0x800, v150
	v_ashrrev_i32_e32 v153, 31, v152
	v_lshl_add_u64 v[152:153], v[152:153], 2, s[52:53]
	global_load_dword v203, v[152:153], off
	v_lshl_add_u64 v[152:153], v[148:149], 0, v[48:49]
	global_load_dword v204, v[152:153], off
	v_add_u32_e32 v152, 0x1000, v150
	v_ashrrev_i32_e32 v153, 31, v152
	v_lshl_add_u64 v[152:153], v[152:153], 2, s[52:53]
	global_load_dword v205, v[152:153], off
	v_lshl_add_u64 v[152:153], v[148:149], 0, v[50:51]
	global_load_dword v206, v[152:153], off
	v_add_u32_e32 v152, 0x1800, v150
	v_ashrrev_i32_e32 v153, 31, v152
	v_lshl_add_u64 v[152:153], v[152:153], 2, s[52:53]
	global_load_dword v207, v[152:153], off
	v_lshl_add_u64 v[152:153], v[148:149], 0, v[52:53]
	global_load_dword v208, v[152:153], off
	v_add_u32_e32 v152, 0x8000, v150
	v_ashrrev_i32_e32 v153, 31, v152
	v_lshl_add_u64 v[152:153], v[152:153], 2, s[52:53]
	global_load_dword v209, v[152:153], off
	v_lshl_add_u64 v[152:153], v[148:149], 0, v[54:55]
	global_load_dword v210, v[152:153], off
	v_add_u32_e32 v152, 0x8800, v150
	v_ashrrev_i32_e32 v153, 31, v152
	v_lshl_add_u64 v[152:153], v[152:153], 2, s[52:53]
	global_load_dword v211, v[152:153], off
	v_lshl_add_u64 v[152:153], v[148:149], 0, v[56:57]
	global_load_dword v212, v[152:153], off
	v_lshl_add_u64 v[152:153], v[148:149], 0, v[58:59]
	global_load_dword v213, v[152:153], off
	v_add_u32_e32 v152, 0x9000, v150
	v_ashrrev_i32_e32 v153, 31, v152
	v_lshl_add_u64 v[152:153], v[152:153], 2, s[52:53]
	global_load_dword v236, v[152:153], off
	v_add_u32_e32 v152, 0x9800, v150
	v_ashrrev_i32_e32 v153, 31, v152
	v_lshl_add_u64 v[152:153], v[152:153], 2, s[52:53]
	global_load_dword v237, v[152:153], off
	v_readlane_b32 s100, v251, 27
	v_readlane_b32 s101, v251, 28
	s_nop 3
	v_lshl_add_u64 v[152:153], s[100:101], 0, v[160:161]
	global_load_dword v238, v[152:153], off
	v_readlane_b32 s100, v251, 31
	v_readlane_b32 s101, v251, 32
	s_nop 3
	v_lshl_add_u64 v[152:153], s[100:101], 0, v[160:161]
	global_load_dword v239, v[152:153], off
	v_readlane_b32 s100, v251, 33
	v_readlane_b32 s101, v251, 34
	s_nop 3
	v_lshl_add_u64 v[152:153], s[100:101], 0, v[160:161]
	global_load_dword v240, v[152:153], off
	global_load_dwordx4 v[4:7], v[16:17], off offset:16
	global_load_dwordx4 v[0:3], v[16:17], off
	global_load_dwordx4 v[8:11], v[18:19], off offset:-4096
	s_nop 0
	global_load_dwordx4 v[12:15], v[12:13], off offset:16
	s_nop 0
	global_load_dwordx4 v[16:19], v[18:19], off
	s_nop 0
	global_load_dwordx4 v[20:23], v[20:21], off offset:16
	s_nop 0
	global_load_dwordx4 v[24:27], v[28:29], off offset:16
	s_nop 0
	global_load_dwordx4 v[28:31], v[28:29], off
	s_nop 0
	global_load_dwordx4 v[34:37], v[104:105], off offset:16
	global_load_dwordx4 v[38:41], v[104:105], off
	v_lshl_add_u64 v[92:93], v[104:105], 0, s[12:13]
	v_add_co_u32_e32 v104, vcc, s0, v104
	v_lshl_add_u64 v[120:121], v[62:63], 0, v[112:113]
	s_nop 0
	v_addc_co_u32_e32 v105, vcc, 0, v105, vcc
	v_lshl_add_u64 v[112:113], s[58:59], 0, v[112:113]
	global_load_dwordx4 v[80:83], v[96:97], off offset:-4096
	s_nop 0
	global_load_dwordx4 v[92:95], v[92:93], off offset:16
	s_nop 0
	global_load_dwordx4 v[96:99], v[96:97], off
	s_nop 0
	global_load_dwordx4 v[100:103], v[100:101], off offset:16
	s_nop 0
	global_load_dwordx4 v[104:107], v[104:105], off
	s_nop 0
	global_load_dwordx4 v[108:111], v[108:109], off offset:16
	s_nop 0
	global_load_dwordx4 v[116:119], v[112:113], off offset:16
	global_load_dwordx4 v[140:143], v[112:113], off
	s_movk_i32 s0, 0x1000
	v_readlane_b32 s76, v251, 17
	v_readlane_b32 s86, v251, 27
	v_readlane_b32 s87, v251, 28
	v_readlane_b32 s77, v251, 18
	v_readlane_b32 s78, v251, 19
	v_readlane_b32 s79, v251, 20
	v_readlane_b32 s80, v251, 21
	v_readlane_b32 s81, v251, 22
	v_readlane_b32 s82, v251, 23
	v_readlane_b32 s83, v251, 24
	v_readlane_b32 s84, v251, 25
	v_readlane_b32 s85, v251, 26
	v_readlane_b32 s88, v251, 29
	v_readlane_b32 s89, v251, 30
	v_readlane_b32 s90, v251, 31
	v_readlane_b32 s91, v251, 32
	s_waitcnt vmcnt(15)
	global_store_dwordx4 v[120:121], v[8:11], off
	s_waitcnt vmcnt(15)
	global_store_dwordx4 v[120:121], v[12:15], off offset:16
	s_waitcnt vmcnt(3)
	v_pk_fma_f32 v[6:7], v[6:7], v[36:37], v[118:119]
	s_waitcnt vmcnt(2)
	v_pk_fma_f32 v[0:1], v[0:1], v[38:39], v[140:141]
	v_pk_fma_f32 v[2:3], v[2:3], v[40:41], v[142:143]
	v_pk_fma_f32 v[0:1], v[8:9], v[80:81], v[0:1]
	v_add_co_u32_e32 v8, vcc, s0, v120
	v_pk_fma_f32 v[4:5], v[4:5], v[34:35], v[116:117]
	s_nop 0
	v_addc_co_u32_e32 v9, vcc, 0, v121, vcc
	v_pk_fma_f32 v[2:3], v[10:11], v[82:83], v[2:3]
	v_pk_fma_f32 v[6:7], v[14:15], v[94:95], v[6:7]
	v_pk_fma_f32 v[4:5], v[12:13], v[92:93], v[4:5]
	v_add_co_u32_e32 v10, vcc, s3, v120
	v_pk_fma_f32 v[2:3], v[18:19], v[98:99], v[2:3]
	v_pk_fma_f32 v[0:1], v[16:17], v[96:97], v[0:1]
	v_pk_fma_f32 v[6:7], v[22:23], v[102:103], v[6:7]
	v_pk_fma_f32 v[4:5], v[20:21], v[100:101], v[4:5]
	v_addc_co_u32_e32 v11, vcc, 0, v121, vcc
	v_pk_fma_f32 v[2:3], v[30:31], v[106:107], v[2:3]
	v_pk_fma_f32 v[0:1], v[28:29], v[104:105], v[0:1]
	v_pk_fma_f32 v[6:7], v[26:27], v[110:111], v[6:7]
	v_pk_fma_f32 v[4:5], v[24:25], v[108:109], v[4:5]
	global_store_dwordx4 v[10:11], v[16:19], off offset:-4096
	global_store_dwordx4 v[8:9], v[20:23], off offset:16
	global_store_dwordx4 v[10:11], v[28:31], off
	global_store_dwordx4 v[10:11], v[24:27], off offset:16
	v_cvt_pk_bf16_f32 v8, v0, v1
	v_cvt_pk_bf16_f32 v9, v2, v3
	v_cvt_pk_bf16_f32 v10, v4, v5
	v_cvt_pk_bf16_f32 v11, v6, v7
	v_add_u32_e32 v12, v85, v164
	ds_write_b128 v12, v[8:11] offset:33792
	ds_write_b128 v86, v[0:3] offset:51200
	ds_write_b128 v86, v[4:7] offset:51216
	v_add_u32_e32 v0, s2, v90
	v_ashrrev_i32_e32 v1, 31, v0
	v_lshlrev_b64 v[0:1], 2, v[0:1]
	v_lshl_add_u64 v[2:3], s[86:87], 0, v[0:1]
	s_waitcnt lgkmcnt(0)
	s_barrier
	v_lshl_add_u64 v[2:3], s[90:91], 0, v[0:1]
	v_readlane_b32 s76, v251, 33
	v_readlane_b32 s77, v251, 34
	s_mov_b32 s0, 0x41700000
	v_lshl_add_u64 v[0:1], s[76:77], 0, v[0:1]
	v_readlane_b32 s78, v251, 35
	v_readlane_b32 s79, v251, 36
	v_readlane_b32 s80, v251, 37
	v_readlane_b32 s81, v251, 38
	v_readlane_b32 s82, v251, 39
	v_readlane_b32 s83, v251, 40
	v_readlane_b32 s84, v251, 41
	v_readlane_b32 s85, v251, 42
	v_readlane_b32 s86, v251, 43
	v_readlane_b32 s87, v251, 44
	v_readlane_b32 s88, v251, 45
	v_readlane_b32 s89, v251, 46
	v_readlane_b32 s90, v251, 47
	v_readlane_b32 s91, v251, 48
	v_mov_b32_e32 v35, v238
	v_mov_b32_e32 v34, v239
	v_mov_b32_e32 v0, v240
	v_cmp_nlt_f32_e32 vcc, s0, v0
	s_and_saveexec_b64 s[0:1], vcc
	s_xor_b64 s[0:1], exec, s[0:1]
	s_cbranch_execz .LBB0_1870
	s_mov_b32 s2, 0xc1700000
	v_cmp_ngt_f32_e32 vcc, s2, v0
	v_xor_b32_e32 v36, 0x80000000, v0
	s_and_saveexec_b64 s[2:3], vcc
	s_xor_b64 s[2:3], exec, s[2:3]
	s_cbranch_execz .LBB0_1869
	v_mul_f32_e32 v0, 0xbfb8aa3b, v0
	v_exp_f32_e32 v0, v0
	s_mov_b32 s7, 0x800000
	v_add_f32_e32 v0, 1.0, v0
	v_cmp_gt_f32_e32 vcc, s7, v0
	s_mov_b32 s7, 0x3f317217
	s_nop 0
	v_cndmask_b32_e64 v1, 0, 32, vcc
	v_ldexp_f32 v0, v0, v1
	v_log_f32_e32 v0, v0
	s_nop 0
	v_mul_f32_e32 v1, 0x3f317217, v0
	v_fma_f32 v1, v0, s7, -v1
	v_fmac_f32_e32 v1, 0x3377d1cf, v0
	s_mov_b32 s7, 0x7f800000
	v_fmac_f32_e32 v1, 0x3f317217, v0
	v_cmp_lt_f32_e64 s[48:49], |v0|, s7
	s_nop 1
	v_cndmask_b32_e64 v0, v0, v1, s[48:49]
	v_cndmask_b32_e32 v1, 0, v250, vcc
	v_sub_f32_e32 v36, v0, v1
